# seam barriers: non-leader L1 invalidate issued before the generation spin; late invalidate kept (conditional) for non-XCD-local fallback
# baseline (speedup 1.0000x reference)
.LBB0_525:
	s_or_b64 exec, exec, s[8:9]
	v_cvt_f32_u32_e32 v6, v4
	s_waitcnt vmcnt(0)
	v_readfirstlane_b32 s0, v5
	v_sub_u32_e32 v5, 0, v4
	v_rcp_iflag_f32_e32 v6, v6
	v_add_u32_e32 v7, s0, v3
	v_mul_f32_e32 v6, 0x4f7ffffe, v6
	v_cvt_u32_f32_e32 v6, v6
	v_mul_lo_u32 v3, v5, v6
	v_mul_hi_u32 v3, v6, v3
	v_add_u32_e32 v3, v6, v3
	v_mul_hi_u32 v3, v7, v3
	v_mul_lo_u32 v5, v3, v4
	v_sub_u32_e32 v5, v7, v5
	v_add_u32_e32 v6, 1, v3
	v_cmp_ge_u32_e32 vcc, v5, v4
	s_nop 1
	v_cndmask_b32_e32 v3, v3, v6, vcc
	v_sub_u32_e32 v6, v5, v4
	v_cndmask_b32_e32 v5, v5, v6, vcc
	v_add_u32_e32 v6, 1, v3
	v_cmp_ge_u32_e32 vcc, v5, v4
	v_add_u32_e32 v5, 1, v7
	s_nop 0
	v_cndmask_b32_e32 v3, v3, v6, vcc
	v_mul_lo_u32 v6, v4, v3
	v_add_u32_e32 v4, v6, v4
	v_cmp_ne_u32_e32 vcc, v5, v4
	s_and_saveexec_b64 s[0:1], vcc
	s_xor_b64 s[0:1], exec, s[0:1]
	s_cbranch_execz .LBB0_539
	s_waitcnt lgkmcnt(0)
	v_mov_b32_e32 v2, 0x2000
	buffer_inv sc1
	global_load_dword v2, v2, s[6:7] offset:1024 sc1
	s_add_u32 s12, s6, 0x2400
	s_addc_u32 s13, s7, 0
	s_waitcnt vmcnt(0)
	v_cmp_eq_u32_e32 vcc, v2, v3
	s_and_saveexec_b64 s[8:9], vcc
	s_cbranch_execz .LBB0_538
	s_add_u32 s10, s34, 0x4200
	s_addc_u32 s11, s35, 0
	s_mov_b32 s3, 1
	s_mov_b64 s[14:15], 0
	v_mov_b32_e32 v2, 0
	s_branch .LBB0_529

.LBB0_538:
	s_or_b64 exec, exec, s[8:9]
	s_waitcnt vmcnt(0)
	v_readlane_b32 s99, v244, 42
	s_cmp_eq_u32 s99, 0
	s_cbranch_scc1 .Lei_1
	buffer_inv sc1
.Lei_1:
	s_waitcnt vmcnt(0)
.LBB0_539:
	s_andn2_saveexec_b64 s[0:1], s[0:1]
	s_cbranch_execz .LBB0_563
	v_readlane_b32 s8, v244, 42
	v_readlane_b32 s9, v244, 43
	s_andn2_b64 vcc, exec, s[8:9]
	s_nop 0
	v_cndmask_b32_e64 v3, 0, 1, s[8:9]
	v_cmp_ne_u32_e64 s[0:1], 1, v3
	s_cbranch_vccnz .LBB0_542
	buffer_wbl2 sc1
	s_waitcnt lgkmcnt(0)

.LBB0_631:
	s_or_b64 exec, exec, s[10:11]
	v_cvt_f32_u32_e32 v6, v4
	s_waitcnt vmcnt(0)
	v_readfirstlane_b32 s0, v5
	v_sub_u32_e32 v5, 0, v4
	v_rcp_iflag_f32_e32 v6, v6
	v_add_u32_e32 v7, s0, v3
	v_mul_f32_e32 v6, 0x4f7ffffe, v6
	v_cvt_u32_f32_e32 v6, v6
	v_mul_lo_u32 v3, v5, v6
	v_mul_hi_u32 v3, v6, v3
	v_add_u32_e32 v3, v6, v3
	v_mul_hi_u32 v3, v7, v3
	v_mul_lo_u32 v5, v3, v4
	v_sub_u32_e32 v5, v7, v5
	v_add_u32_e32 v6, 1, v3
	v_cmp_ge_u32_e32 vcc, v5, v4
	s_nop 1
	v_cndmask_b32_e32 v3, v3, v6, vcc
	v_sub_u32_e32 v6, v5, v4
	v_cndmask_b32_e32 v5, v5, v6, vcc
	v_add_u32_e32 v6, 1, v3
	v_cmp_ge_u32_e32 vcc, v5, v4
	v_add_u32_e32 v5, 1, v7
	s_nop 0
	v_cndmask_b32_e32 v3, v3, v6, vcc
	v_mul_lo_u32 v6, v4, v3
	v_add_u32_e32 v4, v6, v4
	v_cmp_ne_u32_e32 vcc, v5, v4
	s_and_saveexec_b64 s[0:1], vcc
	s_xor_b64 s[0:1], exec, s[0:1]
	s_cbranch_execz .LBB0_645
	s_waitcnt lgkmcnt(0)
	v_mov_b32_e32 v2, 0x2000
	buffer_inv sc1
	global_load_dword v2, v2, s[8:9] offset:1024 sc1
	s_add_u32 s14, s8, 0x2400
	s_addc_u32 s15, s9, 0
	s_waitcnt vmcnt(0)
	v_cmp_eq_u32_e32 vcc, v2, v3
	s_and_saveexec_b64 s[10:11], vcc
	s_cbranch_execz .LBB0_644
	s_add_u32 s12, s34, 0x4200
	s_addc_u32 s13, s35, 0
	s_mov_b32 s3, 1
	s_mov_b64 s[40:41], 0
	v_mov_b32_e32 v2, 0
	s_branch .LBB0_635

.LBB0_644:
	s_or_b64 exec, exec, s[10:11]
	s_waitcnt vmcnt(0)
	v_readlane_b32 s99, v244, 42
	s_cmp_eq_u32 s99, 0
	s_cbranch_scc1 .Lei_2
	buffer_inv sc1
.Lei_2:
	s_waitcnt vmcnt(0)
.LBB0_645:
	s_andn2_saveexec_b64 s[0:1], s[0:1]
	s_cbranch_execz .LBB0_669
	v_readlane_b32 s10, v244, 42
	v_readlane_b32 s11, v244, 43
	s_andn2_b64 vcc, exec, s[10:11]
	s_nop 0
	v_cndmask_b32_e64 v3, 0, 1, s[10:11]
	v_cmp_ne_u32_e64 s[0:1], 1, v3
	s_cbranch_vccnz .LBB0_648
	buffer_wbl2 sc1
	s_waitcnt lgkmcnt(0)

.LBB0_1258:
	s_or_b64 exec, exec, s[8:9]
	v_cvt_f32_u32_e32 v5, v3
	s_waitcnt vmcnt(0)
	v_readfirstlane_b32 s0, v4
	v_sub_u32_e32 v4, 0, v3
	v_rcp_iflag_f32_e32 v5, v5
	v_add_u32_e32 v6, s0, v2
	v_mul_f32_e32 v5, 0x4f7ffffe, v5
	v_cvt_u32_f32_e32 v5, v5
	v_mul_lo_u32 v2, v4, v5
	v_mul_hi_u32 v2, v5, v2
	v_add_u32_e32 v2, v5, v2
	v_mul_hi_u32 v2, v6, v2
	v_mul_lo_u32 v4, v2, v3
	v_sub_u32_e32 v4, v6, v4
	v_add_u32_e32 v5, 1, v2
	v_cmp_ge_u32_e32 vcc, v4, v3
	s_nop 1
	v_cndmask_b32_e32 v2, v2, v5, vcc
	v_sub_u32_e32 v5, v4, v3
	v_cndmask_b32_e32 v4, v4, v5, vcc
	v_add_u32_e32 v5, 1, v2
	v_cmp_ge_u32_e32 vcc, v4, v3
	v_add_u32_e32 v4, 1, v6
	s_nop 0
	v_cndmask_b32_e32 v2, v2, v5, vcc
	v_mul_lo_u32 v5, v3, v2
	v_add_u32_e32 v3, v5, v3
	v_cmp_ne_u32_e32 vcc, v4, v3
	s_and_saveexec_b64 s[0:1], vcc
	s_xor_b64 s[0:1], exec, s[0:1]
	s_cbranch_execz .LBB0_1272
	s_waitcnt lgkmcnt(0)
	v_mov_b32_e32 v1, 0x2000
	buffer_inv sc1
	global_load_dword v1, v1, s[6:7] offset:1024 sc1
	s_add_u32 s12, s6, 0x2400
	s_addc_u32 s13, s7, 0
	s_waitcnt vmcnt(0)
	v_cmp_eq_u32_e32 vcc, v1, v2
	s_and_saveexec_b64 s[8:9], vcc
	s_cbranch_execz .LBB0_1271
	s_add_u32 s10, s34, 0x4200
	s_addc_u32 s11, s35, 0
	s_mov_b32 s3, 1
	s_mov_b64 s[14:15], 0
	v_mov_b32_e32 v1, 0
	s_branch .LBB0_1262

.Lei_3:
	s_waitcnt vmcnt(0)
.LBB0_1272:
	s_andn2_saveexec_b64 s[0:1], s[0:1]
	s_cbranch_execz .LBB0_1296
	v_readlane_b32 s8, v244, 42
	v_readlane_b32 s9, v244, 43
	s_andn2_b64 vcc, exec, s[8:9]
	s_nop 0
	v_cndmask_b32_e64 v2, 0, 1, s[8:9]
	v_cmp_ne_u32_e64 s[0:1], 1, v2
	s_cbranch_vccnz .LBB0_1275
	buffer_wbl2 sc1
	s_waitcnt lgkmcnt(0)

.LBB0_1428:
	s_or_b64 exec, exec, s[8:9]
	v_cvt_f32_u32_e32 v5, v3
	s_waitcnt vmcnt(0)
	v_readfirstlane_b32 s0, v4
	v_sub_u32_e32 v4, 0, v3
	v_rcp_iflag_f32_e32 v5, v5
	v_add_u32_e32 v6, s0, v2
	v_mul_f32_e32 v5, 0x4f7ffffe, v5
	v_cvt_u32_f32_e32 v5, v5
	v_mul_lo_u32 v2, v4, v5
	v_mul_hi_u32 v2, v5, v2
	v_add_u32_e32 v2, v5, v2
	v_mul_hi_u32 v2, v6, v2
	v_mul_lo_u32 v4, v2, v3
	v_sub_u32_e32 v4, v6, v4
	v_add_u32_e32 v5, 1, v2
	v_cmp_ge_u32_e32 vcc, v4, v3
	s_nop 1
	v_cndmask_b32_e32 v2, v2, v5, vcc
	v_sub_u32_e32 v5, v4, v3
	v_cndmask_b32_e32 v4, v4, v5, vcc
	v_add_u32_e32 v5, 1, v2
	v_cmp_ge_u32_e32 vcc, v4, v3
	v_add_u32_e32 v4, 1, v6
	s_nop 0
	v_cndmask_b32_e32 v2, v2, v5, vcc
	v_mul_lo_u32 v5, v3, v2
	v_add_u32_e32 v3, v5, v3
	v_cmp_ne_u32_e32 vcc, v4, v3
	s_and_saveexec_b64 s[0:1], vcc
	s_xor_b64 s[0:1], exec, s[0:1]
	s_cbranch_execz .LBB0_1442
	s_waitcnt lgkmcnt(0)
	v_mov_b32_e32 v1, 0x2000
	buffer_inv sc1
	global_load_dword v1, v1, s[6:7] offset:1024 sc1
	s_add_u32 s14, s6, 0x2400
	s_addc_u32 s15, s7, 0
	s_waitcnt vmcnt(0)
	v_cmp_eq_u32_e32 vcc, v1, v2
	s_and_saveexec_b64 s[8:9], vcc
	s_cbranch_execz .LBB0_1441
	v_readlane_b32 s12, v244, 58
	v_readlane_b32 s13, v244, 59
	s_add_u32 s12, s12, 0x4200
	s_addc_u32 s13, s13, 0
	s_mov_b32 s38, 1
	s_mov_b64 s[18:19], 0
	v_mov_b32_e32 v1, 0
	s_branch .LBB0_1432

.Lei_4:
	s_waitcnt vmcnt(0)
.LBB0_1442:
	s_andn2_saveexec_b64 s[0:1], s[0:1]
	s_cbranch_execz .LBB0_1466
	v_readlane_b32 s8, v244, 42
	v_readlane_b32 s9, v244, 43
	s_andn2_b64 vcc, exec, s[8:9]
	s_nop 0
	v_cndmask_b32_e64 v2, 0, 1, s[8:9]
	v_cmp_ne_u32_e64 s[0:1], 1, v2
	s_cbranch_vccnz .LBB0_1445
	buffer_wbl2 sc1
	s_waitcnt lgkmcnt(0)

.LBB0_1517:
	s_or_b64 exec, exec, s[8:9]
	v_cvt_f32_u32_e32 v5, v3
	s_waitcnt vmcnt(0)
	v_readfirstlane_b32 s6, v4
	v_sub_u32_e32 v4, 0, v3
	v_rcp_iflag_f32_e32 v5, v5
	v_add_u32_e32 v6, s6, v2
	v_mul_f32_e32 v5, 0x4f7ffffe, v5
	v_cvt_u32_f32_e32 v5, v5
	v_mul_lo_u32 v2, v4, v5
	v_mul_hi_u32 v2, v5, v2
	v_add_u32_e32 v2, v5, v2
	v_mul_hi_u32 v2, v6, v2
	v_mul_lo_u32 v4, v2, v3
	v_sub_u32_e32 v4, v6, v4
	v_add_u32_e32 v5, 1, v2
	v_cmp_ge_u32_e32 vcc, v4, v3
	s_nop 1
	v_cndmask_b32_e32 v2, v2, v5, vcc
	v_sub_u32_e32 v5, v4, v3
	v_cndmask_b32_e32 v4, v4, v5, vcc
	v_add_u32_e32 v5, 1, v2
	v_cmp_ge_u32_e32 vcc, v4, v3
	v_add_u32_e32 v4, 1, v6
	s_nop 0
	v_cndmask_b32_e32 v2, v2, v5, vcc
	v_mul_lo_u32 v5, v3, v2
	v_add_u32_e32 v3, v5, v3
	v_cmp_ne_u32_e32 vcc, v4, v3
	s_and_saveexec_b64 s[6:7], vcc
	s_xor_b64 s[6:7], exec, s[6:7]
	s_cbranch_execz .LBB0_1531
	s_waitcnt lgkmcnt(0)
	v_mov_b32_e32 v1, 0x2000
	buffer_inv sc1
	global_load_dword v1, v1, s[4:5] offset:1024 sc1
	s_add_u32 s12, s4, 0x2400
	s_addc_u32 s13, s5, 0
	s_waitcnt vmcnt(0)
	v_cmp_eq_u32_e32 vcc, v1, v2
	s_and_saveexec_b64 s[8:9], vcc
	s_cbranch_execz .LBB0_1530
	s_add_u32 s10, s30, 0x4200
	s_addc_u32 s11, s31, 0
	s_mov_b32 s24, 1
	s_mov_b64 s[14:15], 0
	v_mov_b32_e32 v1, 0
	s_branch .LBB0_1521

.Lei_5:
	s_waitcnt vmcnt(0)
.LBB0_1531:
	s_andn2_saveexec_b64 s[6:7], s[6:7]
	s_cbranch_execz .LBB0_1551
	s_mov_b64 s[6:7], exec
	buffer_wbl2 sc1
	s_waitcnt lgkmcnt(0)
	s_waitcnt vmcnt(0)
	v_mbcnt_lo_u32_b32 v2, s6, 0
	v_mbcnt_hi_u32_b32 v2, s7, v2
	v_cmp_eq_u32_e32 vcc, 0, v2
	s_and_saveexec_b64 s[8:9], vcc
	s_cbranch_execz .LBB0_1534
	s_bcnt1_i32_b64 s6, s[6:7]
	v_mov_b32_e32 v3, 0x7000
	v_mov_b32_e32 v4, s6
	global_atomic_add v3, v3, v4, s[30:31] offset:1024 sc0

.LBB0_1574:
	s_or_b64 exec, exec, s[8:9]
	v_cvt_f32_u32_e32 v4, v2
	s_waitcnt vmcnt(0)
	v_readfirstlane_b32 s6, v3
	v_sub_u32_e32 v3, 0, v2
	v_rcp_iflag_f32_e32 v4, v4
	v_add_u32_e32 v5, s6, v1
	v_mul_f32_e32 v4, 0x4f7ffffe, v4
	v_cvt_u32_f32_e32 v4, v4
	v_mul_lo_u32 v1, v3, v4
	v_mul_hi_u32 v1, v4, v1
	v_add_u32_e32 v1, v4, v1
	v_mul_hi_u32 v1, v5, v1
	v_mul_lo_u32 v3, v1, v2
	v_sub_u32_e32 v3, v5, v3
	v_add_u32_e32 v4, 1, v1
	v_cmp_ge_u32_e32 vcc, v3, v2
	s_nop 1
	v_cndmask_b32_e32 v1, v1, v4, vcc
	v_sub_u32_e32 v4, v3, v2
	v_cndmask_b32_e32 v3, v3, v4, vcc
	v_add_u32_e32 v4, 1, v1
	v_cmp_ge_u32_e32 vcc, v3, v2
	v_add_u32_e32 v3, 1, v5
	s_nop 0
	v_cndmask_b32_e32 v1, v1, v4, vcc
	v_mul_lo_u32 v4, v2, v1
	v_add_u32_e32 v2, v4, v2
	v_cmp_ne_u32_e32 vcc, v3, v2
	s_and_saveexec_b64 s[6:7], vcc
	s_xor_b64 s[6:7], exec, s[6:7]
	s_cbranch_execz .LBB0_1588
	v_mov_b32_e32 v2, 0x2000
	buffer_inv sc1
	global_load_dword v2, v2, s[4:5] offset:1024 sc1
	s_add_u32 s12, s4, 0x2400
	s_addc_u32 s13, s5, 0
	s_waitcnt vmcnt(0)
	v_cmp_eq_u32_e32 vcc, v2, v1
	s_and_saveexec_b64 s[8:9], vcc
	s_cbranch_execz .LBB0_1587
	s_add_u32 s10, s30, 0x4200
	s_addc_u32 s11, s31, 0
	s_mov_b32 s24, 1
	s_mov_b64 s[14:15], 0
	v_mov_b32_e32 v2, 0
	s_branch .LBB0_1578

.Lei_6:
	s_waitcnt vmcnt(0)
.LBB0_1588:
	s_andn2_saveexec_b64 s[6:7], s[6:7]
	s_cbranch_execz .LBB0_1592
	s_mov_b64 s[6:7], exec
	s_waitcnt vmcnt(0)
	v_mbcnt_lo_u32_b32 v1, s6, 0
	v_mbcnt_hi_u32_b32 v1, s7, v1
	v_cmp_eq_u32_e32 vcc, 0, v1
	buffer_inv sc1
	s_and_saveexec_b64 s[8:9], vcc
	s_cbranch_execz .LBB0_1591
	s_bcnt1_i32_b64 s6, s[6:7]
	v_mov_b32_e32 v1, 0x2000
	v_mov_b32_e32 v2, s6
	global_atomic_add v1, v2, s[4:5] offset:1024

.LBB0_1670:
	s_or_b64 exec, exec, s[10:11]
	v_cvt_f32_u32_e32 v5, v3
	s_waitcnt vmcnt(0)
	v_readfirstlane_b32 s0, v4
	v_sub_u32_e32 v4, 0, v3
	v_rcp_iflag_f32_e32 v5, v5
	v_add_u32_e32 v6, s0, v2
	v_mul_f32_e32 v5, 0x4f7ffffe, v5
	v_cvt_u32_f32_e32 v5, v5
	v_mul_lo_u32 v2, v4, v5
	v_mul_hi_u32 v2, v5, v2
	v_add_u32_e32 v2, v5, v2
	v_mul_hi_u32 v2, v6, v2
	v_mul_lo_u32 v4, v2, v3
	v_sub_u32_e32 v4, v6, v4
	v_add_u32_e32 v5, 1, v2
	v_cmp_ge_u32_e32 vcc, v4, v3
	s_nop 1
	v_cndmask_b32_e32 v2, v2, v5, vcc
	v_sub_u32_e32 v5, v4, v3
	v_cndmask_b32_e32 v4, v4, v5, vcc
	v_add_u32_e32 v5, 1, v2
	v_cmp_ge_u32_e32 vcc, v4, v3
	v_add_u32_e32 v4, 1, v6
	s_nop 0
	v_cndmask_b32_e32 v2, v2, v5, vcc
	v_mul_lo_u32 v5, v3, v2
	v_add_u32_e32 v3, v5, v3
	v_cmp_ne_u32_e32 vcc, v4, v3
	s_and_saveexec_b64 s[0:1], vcc
	s_xor_b64 s[0:1], exec, s[0:1]
	s_cbranch_execz .LBB0_1684
	s_waitcnt lgkmcnt(0)
	v_mov_b32_e32 v1, 0x2000
	buffer_inv sc1
	global_load_dword v1, v1, s[8:9] offset:1024 sc1
	s_add_u32 s14, s8, 0x2400
	s_addc_u32 s15, s9, 0
	s_waitcnt vmcnt(0)
	v_cmp_eq_u32_e32 vcc, v1, v2
	s_and_saveexec_b64 s[10:11], vcc
	s_cbranch_execz .LBB0_1683
	s_add_u32 s12, s34, 0x4200
	s_addc_u32 s13, s35, 0
	s_mov_b32 s3, 1
	s_mov_b64 s[16:17], 0
	v_mov_b32_e32 v1, 0
	s_branch .LBB0_1674

.Lei_7:
	s_waitcnt vmcnt(0)
.LBB0_1684:
	s_andn2_saveexec_b64 s[0:1], s[0:1]
	s_cbranch_execz .LBB0_1708
	v_readlane_b32 s10, v244, 42
	v_readlane_b32 s11, v244, 43
	s_andn2_b64 vcc, exec, s[10:11]
	s_nop 0
	v_cndmask_b32_e64 v2, 0, 1, s[10:11]
	v_cmp_ne_u32_e64 s[0:1], 1, v2
	s_cbranch_vccnz .LBB0_1687
	buffer_wbl2 sc1
	s_waitcnt lgkmcnt(0)

.Lei_8:
	s_waitcnt vmcnt(0)
.LBB0_1764:
	s_andn2_saveexec_b64 s[0:1], s[0:1]
	s_cbranch_execz .LBB0_1788
	v_readlane_b32 s8, v244, 42
	v_readlane_b32 s9, v244, 43
	s_andn2_b64 vcc, exec, s[8:9]
	s_nop 0
	v_cndmask_b32_e64 v2, 0, 1, s[8:9]
	v_cmp_ne_u32_e64 s[0:1], 1, v2
	s_cbranch_vccnz .LBB0_1767
	buffer_wbl2 sc1
	s_waitcnt lgkmcnt(0)

	.amdhsa_kernel _Z6mk_fwd4Args
		.amdhsa_group_segment_fixed_size 0
		.amdhsa_private_segment_fixed_size 0
		.amdhsa_kernarg_size 472
		.amdhsa_user_sgpr_count 2
		.amdhsa_user_sgpr_dispatch_ptr 0
		.amdhsa_user_sgpr_queue_ptr 0
		.amdhsa_user_sgpr_kernarg_segment_ptr 1
		.amdhsa_user_sgpr_dispatch_id 0
		.amdhsa_user_sgpr_kernarg_preload_length 0
		.amdhsa_user_sgpr_kernarg_preload_offset 0
		.amdhsa_user_sgpr_private_segment_size 0
		.amdhsa_uses_dynamic_stack 0
		.amdhsa_enable_private_segment 0
		.amdhsa_system_sgpr_workgroup_id_x 1
		.amdhsa_system_sgpr_workgroup_id_y 0
		.amdhsa_system_sgpr_workgroup_id_z 0
		.amdhsa_system_sgpr_workgroup_info 0
		.amdhsa_system_vgpr_workitem_id 0
		.amdhsa_next_free_vgpr 245
		.amdhsa_next_free_sgpr 102
		.amdhsa_accum_offset 248
		.amdhsa_reserve_vcc 1
		.amdhsa_float_round_mode_32 0
		.amdhsa_float_round_mode_16_64 0
		.amdhsa_float_denorm_mode_32 3
		.amdhsa_float_denorm_mode_16_64 3
		.amdhsa_dx10_clamp 1
		.amdhsa_ieee_mode 1
		.amdhsa_fp16_overflow 0
		.amdhsa_tg_split 0
		.amdhsa_exception_fp_ieee_invalid_op 0
		.amdhsa_exception_fp_denorm_src 0
		.amdhsa_exception_fp_ieee_div_zero 0
		.amdhsa_exception_fp_ieee_overflow 0
		.amdhsa_exception_fp_ieee_underflow 0
		.amdhsa_exception_fp_ieee_inexact 0
		.amdhsa_exception_int_div_zero 0
	.end_amdhsa_kernel

amdhsa.kernels:
  - .agpr_count:     0
    .args:
      - .offset:         0
        .size:           216
        .value_kind:     by_value
      - .offset:         216
        .size:           4
        .value_kind:     hidden_block_count_x
      - .offset:         220
        .size:           4
        .value_kind:     hidden_block_count_y
      - .offset:         224
        .size:           4
        .value_kind:     hidden_block_count_z
      - .offset:         228
        .size:           2
        .value_kind:     hidden_group_size_x
      - .offset:         230
        .size:           2
        .value_kind:     hidden_group_size_y
      - .offset:         232
        .size:           2
        .value_kind:     hidden_group_size_z
      - .offset:         234
        .size:           2
        .value_kind:     hidden_remainder_x
      - .offset:         236
        .size:           2
        .value_kind:     hidden_remainder_y
      - .offset:         238
        .size:           2
        .value_kind:     hidden_remainder_z
      - .offset:         256
        .size:           8
        .value_kind:     hidden_global_offset_x
      - .offset:         264
        .size:           8
        .value_kind:     hidden_global_offset_y
      - .offset:         272
        .size:           8
        .value_kind:     hidden_global_offset_z
      - .offset:         280
        .size:           2
        .value_kind:     hidden_grid_dims
      - .offset:         336
        .size:           4
        .value_kind:     hidden_dynamic_lds_size
    .group_segment_fixed_size: 0
    .kernarg_segment_align: 8
    .kernarg_segment_size: 472
    .language:       OpenCL C
    .language_version:
      - 2
      - 0
    .max_flat_workgroup_size: 512
    .name:           _Z6mk_fwd4Args
    .private_segment_fixed_size: 0
    .sgpr_count:     108
    .sgpr_spill_count: 66
    .symbol:         _Z6mk_fwd4Args.kd
    .uniform_work_group_size: 1
    .uses_dynamic_stack: false
    .vgpr_count:     245
    .vgpr_spill_count: 0
    .wavefront_size: 64
